# v066 + uq/ukv/G_OUT/G_UP K-loops: the four kstep-advanced LDS-DMA pieces use a per-tile precomputed voffset+0x80 VGPR (plain saddr form); no 64-bit VALU address adds left in those loops
# speedup vs baseline: 1.0052x; 1.0052x over previous
.LBB0_635:
	s_ashr_i32 s43, s42, 31
	s_lshl_b64 s[44:45], s[42:43], 18
	s_add_u32 s44, s2, s44
	s_addc_u32 s45, s3, s45
	s_and_b64 s[50:51], s[40:41], exec
	s_cselect_b32 s35, s45, s69
	s_cselect_b32 s43, s44, s68
	s_ashr_i32 s31, s30, 31
	s_lshl_b64 s[50:51], s[30:31], 18
	s_add_u32 s52, s16, s50
	s_addc_u32 s53, s17, s51
	s_and_b64 s[50:51], s[40:41], exec
	s_cselect_b32 s31, s53, s83
	s_cselect_b32 s50, s52, s82
	s_add_u32 s68, s68, 0x20080
	s_addc_u32 s69, s69, 0
	s_add_u32 s51, s82, 0x100
	v_mov_b32_e32 v0, 0
	s_addc_u32 s54, s83, 0
	s_mov_b32 s55, -2
	v_mov_b32_e32 v1, v0
	v_mov_b32_e32 v2, v0
	v_mov_b32_e32 v3, v0
	v_mov_b32_e32 v4, v0
	v_mov_b32_e32 v5, v0
	v_mov_b32_e32 v6, v0
	v_mov_b32_e32 v7, v0
	v_mov_b32_e32 v8, v0
	v_mov_b32_e32 v9, v0
	v_mov_b32_e32 v10, v0
	v_mov_b32_e32 v11, v0
	v_mov_b32_e32 v12, v0
	v_mov_b32_e32 v13, v0
	v_mov_b32_e32 v14, v0
	v_mov_b32_e32 v15, v0
	v_mov_b32_e32 v24, v0
	v_mov_b32_e32 v25, v0
	v_mov_b32_e32 v26, v0
	v_mov_b32_e32 v27, v0
	v_mov_b32_e32 v28, v0
	v_mov_b32_e32 v29, v0
	v_mov_b32_e32 v30, v0
	v_mov_b32_e32 v31, v0
	v_mov_b32_e32 v40, v0
	v_mov_b32_e32 v41, v0
	v_mov_b32_e32 v42, v0
	v_mov_b32_e32 v43, v0
	v_mov_b32_e32 v44, v0
	v_mov_b32_e32 v45, v0
	v_mov_b32_e32 v46, v0
	v_mov_b32_e32 v47, v0
	v_mov_b32_e32 v16, v0
	v_mov_b32_e32 v17, v0
	v_mov_b32_e32 v18, v0
	v_mov_b32_e32 v19, v0
	v_mov_b32_e32 v20, v0
	v_mov_b32_e32 v21, v0
	v_mov_b32_e32 v22, v0
	v_mov_b32_e32 v23, v0
	v_mov_b32_e32 v32, v0
	v_mov_b32_e32 v33, v0
	v_mov_b32_e32 v34, v0
	v_mov_b32_e32 v35, v0
	v_mov_b32_e32 v36, v0
	v_mov_b32_e32 v37, v0
	v_mov_b32_e32 v38, v0
	v_mov_b32_e32 v39, v0
	v_mov_b32_e32 v48, v0
	v_mov_b32_e32 v49, v0
	v_mov_b32_e32 v50, v0
	v_mov_b32_e32 v51, v0
	v_mov_b32_e32 v52, v0
	v_mov_b32_e32 v53, v0
	v_mov_b32_e32 v54, v0
	v_mov_b32_e32 v55, v0
	v_mov_b32_e32 v56, v0
	v_mov_b32_e32 v57, v0
	v_mov_b32_e32 v58, v0
	v_mov_b32_e32 v59, v0
	v_mov_b32_e32 v60, v0
	v_mov_b32_e32 v61, v0
	v_mov_b32_e32 v62, v0
	v_mov_b32_e32 v63, v0
	v_mov_b32_e32 v64, v0
	v_mov_b32_e32 v65, v0
	v_mov_b32_e32 v66, v0
	v_mov_b32_e32 v67, v0
	v_mov_b32_e32 v68, v0
	v_mov_b32_e32 v69, v0
	v_mov_b32_e32 v70, v0
	v_mov_b32_e32 v71, v0
	v_mov_b32_e32 v72, v0
	v_mov_b32_e32 v73, v0
	v_mov_b32_e32 v74, v0
	v_mov_b32_e32 v75, v0
	v_mov_b32_e32 v76, v0
	v_mov_b32_e32 v77, v0
	v_mov_b32_e32 v78, v0
	v_mov_b32_e32 v79, v0
	v_mov_b32_e32 v88, v0
	v_mov_b32_e32 v89, v0
	v_mov_b32_e32 v90, v0
	v_mov_b32_e32 v91, v0
	v_mov_b32_e32 v92, v0
	v_mov_b32_e32 v93, v0
	v_mov_b32_e32 v94, v0
	v_mov_b32_e32 v95, v0
	v_mov_b32_e32 v106, v0
	v_mov_b32_e32 v107, v0
	v_mov_b32_e32 v108, v0
	v_mov_b32_e32 v109, v0
	v_mov_b32_e32 v110, v0
	v_mov_b32_e32 v111, v0
	v_mov_b32_e32 v112, v0
	v_mov_b32_e32 v113, v0
	v_mov_b32_e32 v80, v0
	v_mov_b32_e32 v81, v0
	v_mov_b32_e32 v82, v0
	v_mov_b32_e32 v83, v0
	v_mov_b32_e32 v84, v0
	v_mov_b32_e32 v85, v0
	v_mov_b32_e32 v86, v0
	v_mov_b32_e32 v87, v0
	v_mov_b32_e32 v98, v0
	v_mov_b32_e32 v99, v0
	v_mov_b32_e32 v100, v0
	v_mov_b32_e32 v101, v0
	v_mov_b32_e32 v102, v0
	v_mov_b32_e32 v103, v0
	v_mov_b32_e32 v104, v0
	v_mov_b32_e32 v105, v0
	v_mov_b32_e32 v114, v0
	v_mov_b32_e32 v115, v0
	v_mov_b32_e32 v116, v0
	v_mov_b32_e32 v117, v0
	v_mov_b32_e32 v118, v0
	v_mov_b32_e32 v119, v0
	v_mov_b32_e32 v120, v0
	v_mov_b32_e32 v121, v0
	v_mov_b32_e32 v122, v0
	v_mov_b32_e32 v123, v0
	v_mov_b32_e32 v124, v0
	v_mov_b32_e32 v125, v0
	v_mov_b32_e32 v126, v0
	v_mov_b32_e32 v127, v0
	v_mov_b32_e32 v128, v0
	v_mov_b32_e32 v129, v0
	v_add_u32_e32 v155, 0x80, v96
	v_add_u32_e32 v157, 0x80, v130
	v_add_u32_e32 v199, 0x80, v134
	v_add_u32_e32 v203, 0x80, v132

.Lrx_uq_1:
	s_waitcnt vmcnt(24)
	v_mov_b32_e32 v243, 0
	s_waitcnt lgkmcnt(0)
	s_setprio 1
	s_barrier
	v_mfma_f32_16x16x32_bf16 v[60:63], v[146:149], v[182:185], v[60:63]
	v_mfma_f32_16x16x32_bf16 v[56:59], v[158:161], v[182:185], v[56:59]
	v_mfma_f32_16x16x32_bf16 v[52:55], v[146:149], v[190:193], v[52:55]
	v_mfma_f32_16x16x32_bf16 v[48:51], v[158:161], v[190:193], v[48:51]
	v_mfma_f32_16x16x32_bf16 v[36:39], v[146:149], v[210:213], v[36:39]
	v_mfma_f32_16x16x32_bf16 v[32:35], v[158:161], v[210:213], v[32:35]
	v_mfma_f32_16x16x32_bf16 v[20:23], v[146:149], v[218:221], v[20:23]
	v_mfma_f32_16x16x32_bf16 v[16:19], v[158:161], v[218:221], v[16:19]
	v_mfma_f32_16x16x32_bf16 v[60:63], v[150:153], v[186:189], v[60:63]
	v_mfma_f32_16x16x32_bf16 v[56:59], v[162:165], v[186:189], v[56:59]
	v_mfma_f32_16x16x32_bf16 v[52:55], v[150:153], v[194:197], v[52:55]
	v_mfma_f32_16x16x32_bf16 v[48:51], v[162:165], v[194:197], v[48:51]
	v_mfma_f32_16x16x32_bf16 v[36:39], v[150:153], v[214:217], v[36:39]
	v_mfma_f32_16x16x32_bf16 v[32:35], v[162:165], v[214:217], v[32:35]
	v_mfma_f32_16x16x32_bf16 v[20:23], v[150:153], v[222:225], v[20:23]
	v_mfma_f32_16x16x32_bf16 v[16:19], v[162:165], v[222:225], v[16:19]
	v_mfma_f32_16x16x32_bf16 v[44:47], v[166:169], v[182:185], v[44:47]
	v_mfma_f32_16x16x32_bf16 v[40:43], v[174:177], v[182:185], v[40:43]
	v_mfma_f32_16x16x32_bf16 v[28:31], v[166:169], v[190:193], v[28:31]
	v_mfma_f32_16x16x32_bf16 v[24:27], v[174:177], v[190:193], v[24:27]
	v_mfma_f32_16x16x32_bf16 v[12:15], v[166:169], v[210:213], v[12:15]
	v_mfma_f32_16x16x32_bf16 v[8:11], v[174:177], v[210:213], v[8:11]
	v_mfma_f32_16x16x32_bf16 v[4:7], v[166:169], v[218:221], v[4:7]
	v_mfma_f32_16x16x32_bf16 v[0:3], v[174:177], v[218:221], v[0:3]
	v_mfma_f32_16x16x32_bf16 v[44:47], v[170:173], v[186:189], v[44:47]
	v_mfma_f32_16x16x32_bf16 v[40:43], v[178:181], v[186:189], v[40:43]
	v_mfma_f32_16x16x32_bf16 v[28:31], v[170:173], v[194:197], v[28:31]
	v_mfma_f32_16x16x32_bf16 v[24:27], v[178:181], v[194:197], v[24:27]
	v_mfma_f32_16x16x32_bf16 v[12:15], v[170:173], v[214:217], v[12:15]
	v_mfma_f32_16x16x32_bf16 v[8:11], v[178:181], v[214:217], v[8:11]
	v_mfma_f32_16x16x32_bf16 v[4:7], v[170:173], v[222:225], v[4:7]
	v_mfma_f32_16x16x32_bf16 v[0:3], v[178:181], v[222:225], v[0:3]
	s_barrier
	s_setprio 0
	s_add_i32 s58, 0, 0x18000
	v_add_u32_e32 v145, s58, v142
	s_add_i32 s59, 0, 0x1c000
	ds_read_b128 v[146:149], v145
	ds_read_b128 v[150:153], v145 offset:1024
	ds_read_b128 v[158:161], v145 offset:2048
	ds_read_b128 v[162:165], v145 offset:3072
	v_add_u32_e32 v145, s59, v142
	ds_read_b128 v[166:169], v145
	ds_read_b128 v[170:173], v145 offset:1024
	ds_read_b128 v[174:177], v145 offset:2048
	ds_read_b128 v[178:181], v145 offset:3072
	s_add_u32 s56, s84, 0x20000
	s_addc_u32 s57, s85, 0
	s_mov_b32 m0, s18
	ds_read_b128 v[182:185], v144 offset:32768
	ds_read_b128 v[186:189], v144 offset:33792
	ds_read_b128 v[190:193], v144 offset:34816
	ds_read_b128 v[194:197], v144 offset:35840
	ds_read_b128 v[210:213], v144 offset:36864
	ds_read_b128 v[214:217], v144 offset:37888
	ds_read_b128 v[218:221], v144 offset:38912
	ds_read_b128 v[222:225], v144 offset:39936
	global_load_lds_dwordx4 v134, s[56:57]
	s_mov_b32 m0, s20
	s_nop 0
	global_load_lds_dwordx4 v132, s[56:57]
	s_waitcnt vmcnt(8)
	s_waitcnt lgkmcnt(0)
	s_setprio 1
	s_barrier
	v_mfma_f32_16x16x32_bf16 v[126:129], v[146:149], v[182:185], v[126:129]
	v_mfma_f32_16x16x32_bf16 v[122:125], v[158:161], v[182:185], v[122:125]
	v_mfma_f32_16x16x32_bf16 v[118:121], v[146:149], v[190:193], v[118:121]
	v_mfma_f32_16x16x32_bf16 v[114:117], v[158:161], v[190:193], v[114:117]
	v_mfma_f32_16x16x32_bf16 v[102:105], v[146:149], v[210:213], v[102:105]
	v_mfma_f32_16x16x32_bf16 v[98:101], v[158:161], v[210:213], v[98:101]
	v_mfma_f32_16x16x32_bf16 v[84:87], v[146:149], v[218:221], v[84:87]
	v_mfma_f32_16x16x32_bf16 v[80:83], v[158:161], v[218:221], v[80:83]
	v_mfma_f32_16x16x32_bf16 v[126:129], v[150:153], v[186:189], v[126:129]
	v_mfma_f32_16x16x32_bf16 v[122:125], v[162:165], v[186:189], v[122:125]
	v_mfma_f32_16x16x32_bf16 v[118:121], v[150:153], v[194:197], v[118:121]
	v_mfma_f32_16x16x32_bf16 v[114:117], v[162:165], v[194:197], v[114:117]
	v_mfma_f32_16x16x32_bf16 v[102:105], v[150:153], v[214:217], v[102:105]
	v_mfma_f32_16x16x32_bf16 v[98:101], v[162:165], v[214:217], v[98:101]
	v_mfma_f32_16x16x32_bf16 v[84:87], v[150:153], v[222:225], v[84:87]
	v_mfma_f32_16x16x32_bf16 v[80:83], v[162:165], v[222:225], v[80:83]
	v_mfma_f32_16x16x32_bf16 v[110:113], v[166:169], v[182:185], v[110:113]
	v_mfma_f32_16x16x32_bf16 v[106:109], v[174:177], v[182:185], v[106:109]
	v_mfma_f32_16x16x32_bf16 v[92:95], v[166:169], v[190:193], v[92:95]
	v_mfma_f32_16x16x32_bf16 v[88:91], v[174:177], v[190:193], v[88:91]
	v_mfma_f32_16x16x32_bf16 v[76:79], v[166:169], v[210:213], v[76:79]
	v_mfma_f32_16x16x32_bf16 v[72:75], v[174:177], v[210:213], v[72:75]
	v_mfma_f32_16x16x32_bf16 v[68:71], v[166:169], v[218:221], v[68:71]
	v_mfma_f32_16x16x32_bf16 v[64:67], v[174:177], v[218:221], v[64:67]
	v_mfma_f32_16x16x32_bf16 v[110:113], v[170:173], v[186:189], v[110:113]
	v_mfma_f32_16x16x32_bf16 v[106:109], v[178:181], v[186:189], v[106:109]
	v_mfma_f32_16x16x32_bf16 v[92:95], v[170:173], v[194:197], v[92:95]
	v_mfma_f32_16x16x32_bf16 v[88:91], v[178:181], v[194:197], v[88:91]
	v_mfma_f32_16x16x32_bf16 v[76:79], v[170:173], v[214:217], v[76:79]
	v_mfma_f32_16x16x32_bf16 v[72:75], v[178:181], v[214:217], v[72:75]
	v_mfma_f32_16x16x32_bf16 v[68:71], v[170:173], v[222:225], v[68:71]
	v_mfma_f32_16x16x32_bf16 v[64:67], v[178:181], v[222:225], v[64:67]
	s_barrier
	s_setprio 0
	s_add_i32 s56, s58, s75
	s_mov_b32 m0, s56
	ds_read_b128 v[182:185], v144 offset:49152
	ds_read_b128 v[186:189], v144 offset:50176
	ds_read_b128 v[190:193], v144 offset:51200
	ds_read_b128 v[194:197], v144 offset:52224
	ds_read_b128 v[210:213], v144 offset:53248
	ds_read_b128 v[214:217], v144 offset:54272
	ds_read_b128 v[218:221], v144 offset:55296
	ds_read_b128 v[222:225], v144 offset:56320
	global_load_lds_dwordx4 v155, s[82:83]
	s_add_i32 m0, s56, 0x2000
	s_add_u32 s56, s82, 0x20080
	s_addc_u32 s57, s83, 0
	s_add_i32 s58, s59, s75
	global_load_lds_dwordx4 v157, s[82:83]
	s_mov_b32 m0, s58
	s_nop 0
	global_load_lds_dwordx4 v96, s[56:57]
	s_add_i32 m0, s58, 0x2000
	s_nop 0
	global_load_lds_dwordx4 v130, s[56:57]
	s_mov_b32 m0, s26
	s_nop 0
	global_load_lds_dwordx4 v199, s[84:85]
	s_mov_b32 m0, s27
	s_nop 0
	global_load_lds_dwordx4 v203, s[84:85]
	s_waitcnt vmcnt(8)
	s_waitcnt lgkmcnt(0)
	s_setprio 1
	s_barrier
	v_mfma_f32_16x16x32_bf16 v[60:63], v[146:149], v[182:185], v[60:63]
	v_mfma_f32_16x16x32_bf16 v[56:59], v[158:161], v[182:185], v[56:59]
	v_mfma_f32_16x16x32_bf16 v[52:55], v[146:149], v[190:193], v[52:55]
	v_mfma_f32_16x16x32_bf16 v[48:51], v[158:161], v[190:193], v[48:51]
	v_mfma_f32_16x16x32_bf16 v[36:39], v[146:149], v[210:213], v[36:39]
	v_mfma_f32_16x16x32_bf16 v[32:35], v[158:161], v[210:213], v[32:35]
	v_mfma_f32_16x16x32_bf16 v[20:23], v[146:149], v[218:221], v[20:23]
	v_mfma_f32_16x16x32_bf16 v[16:19], v[158:161], v[218:221], v[16:19]
	v_mfma_f32_16x16x32_bf16 v[60:63], v[150:153], v[186:189], v[60:63]
	v_mfma_f32_16x16x32_bf16 v[56:59], v[162:165], v[186:189], v[56:59]
	v_mfma_f32_16x16x32_bf16 v[52:55], v[150:153], v[194:197], v[52:55]
	v_mfma_f32_16x16x32_bf16 v[48:51], v[162:165], v[194:197], v[48:51]
	v_mfma_f32_16x16x32_bf16 v[36:39], v[150:153], v[214:217], v[36:39]
	v_mfma_f32_16x16x32_bf16 v[32:35], v[162:165], v[214:217], v[32:35]
	v_mfma_f32_16x16x32_bf16 v[20:23], v[150:153], v[222:225], v[20:23]
	v_mfma_f32_16x16x32_bf16 v[16:19], v[162:165], v[222:225], v[16:19]
	v_mfma_f32_16x16x32_bf16 v[44:47], v[166:169], v[182:185], v[44:47]
	v_mfma_f32_16x16x32_bf16 v[40:43], v[174:177], v[182:185], v[40:43]
	v_mfma_f32_16x16x32_bf16 v[28:31], v[166:169], v[190:193], v[28:31]
	v_mfma_f32_16x16x32_bf16 v[24:27], v[174:177], v[190:193], v[24:27]
	v_mfma_f32_16x16x32_bf16 v[12:15], v[166:169], v[210:213], v[12:15]
	v_mfma_f32_16x16x32_bf16 v[8:11], v[174:177], v[210:213], v[8:11]
	v_mfma_f32_16x16x32_bf16 v[4:7], v[166:169], v[218:221], v[4:7]
	v_mfma_f32_16x16x32_bf16 v[0:3], v[174:177], v[218:221], v[0:3]
	v_mfma_f32_16x16x32_bf16 v[44:47], v[170:173], v[186:189], v[44:47]
	v_mfma_f32_16x16x32_bf16 v[40:43], v[178:181], v[186:189], v[40:43]
	v_mfma_f32_16x16x32_bf16 v[28:31], v[170:173], v[194:197], v[28:31]
	v_mfma_f32_16x16x32_bf16 v[24:27], v[178:181], v[194:197], v[24:27]
	v_mfma_f32_16x16x32_bf16 v[12:15], v[170:173], v[214:217], v[12:15]
	v_mfma_f32_16x16x32_bf16 v[8:11], v[178:181], v[214:217], v[8:11]
	v_mfma_f32_16x16x32_bf16 v[4:7], v[170:173], v[222:225], v[4:7]
	v_mfma_f32_16x16x32_bf16 v[0:3], v[178:181], v[222:225], v[0:3]
	s_barrier
	s_setprio 0
	s_add_i32 s55, s55, 2
	s_add_u32 s68, s68, 0x100
	s_addc_u32 s69, s69, 0
	s_add_u32 s51, s51, 0x100
	s_addc_u32 s54, s54, 0
	s_cmp_gt_u32 s55, 5
	s_cbranch_scc0 .LBB0_636
	v_mov_b32_e32 v243, 1
	v_readlane_b32 s6, v251, 54
	v_readlane_b32 s7, v251, 55
	s_and_b64 vcc, exec, s[6:7]
	s_cbranch_vccz .LBB0_639
	s_barrier

.LBB0_655:
	s_ashr_i32 s43, s42, 31
	s_lshl_b64 s[44:45], s[42:43], 18
	s_add_u32 s44, s10, s44
	s_addc_u32 s45, s12, s45
	s_and_b64 s[52:53], s[40:41], exec
	s_cselect_b32 s43, s45, s69
	s_cselect_b32 s51, s44, s68
	s_ashr_i32 s31, s30, 31
	s_lshl_b64 s[52:53], s[30:31], 18
	s_add_u32 s52, s2, s52
	s_addc_u32 s53, s3, s53
	s_and_b64 s[54:55], s[40:41], exec
	s_cselect_b32 s31, s53, s83
	s_cselect_b32 s54, s52, s82
	s_add_u32 s68, s68, 0x20080
	s_addc_u32 s69, s69, 0
	s_add_u32 s55, s82, 0x100
	v_mov_b32_e32 v0, 0
	s_addc_u32 s56, s83, 0
	s_mov_b32 s57, -2
	v_mov_b32_e32 v1, v0
	v_mov_b32_e32 v2, v0
	v_mov_b32_e32 v3, v0
	v_mov_b32_e32 v4, v0
	v_mov_b32_e32 v5, v0
	v_mov_b32_e32 v6, v0
	v_mov_b32_e32 v7, v0
	v_mov_b32_e32 v8, v0
	v_mov_b32_e32 v9, v0
	v_mov_b32_e32 v10, v0
	v_mov_b32_e32 v11, v0
	v_mov_b32_e32 v12, v0
	v_mov_b32_e32 v13, v0
	v_mov_b32_e32 v14, v0
	v_mov_b32_e32 v15, v0
	v_mov_b32_e32 v24, v0
	v_mov_b32_e32 v25, v0
	v_mov_b32_e32 v26, v0
	v_mov_b32_e32 v27, v0
	v_mov_b32_e32 v28, v0
	v_mov_b32_e32 v29, v0
	v_mov_b32_e32 v30, v0
	v_mov_b32_e32 v31, v0
	v_mov_b32_e32 v40, v0
	v_mov_b32_e32 v41, v0
	v_mov_b32_e32 v42, v0
	v_mov_b32_e32 v43, v0
	v_mov_b32_e32 v44, v0
	v_mov_b32_e32 v45, v0
	v_mov_b32_e32 v46, v0
	v_mov_b32_e32 v47, v0
	v_mov_b32_e32 v16, v0
	v_mov_b32_e32 v17, v0
	v_mov_b32_e32 v18, v0
	v_mov_b32_e32 v19, v0
	v_mov_b32_e32 v20, v0
	v_mov_b32_e32 v21, v0
	v_mov_b32_e32 v22, v0
	v_mov_b32_e32 v23, v0
	v_mov_b32_e32 v32, v0
	v_mov_b32_e32 v33, v0
	v_mov_b32_e32 v34, v0
	v_mov_b32_e32 v35, v0
	v_mov_b32_e32 v36, v0
	v_mov_b32_e32 v37, v0
	v_mov_b32_e32 v38, v0
	v_mov_b32_e32 v39, v0
	v_mov_b32_e32 v48, v0
	v_mov_b32_e32 v49, v0
	v_mov_b32_e32 v50, v0
	v_mov_b32_e32 v51, v0
	v_mov_b32_e32 v52, v0
	v_mov_b32_e32 v53, v0
	v_mov_b32_e32 v54, v0
	v_mov_b32_e32 v55, v0
	v_mov_b32_e32 v56, v0
	v_mov_b32_e32 v57, v0
	v_mov_b32_e32 v58, v0
	v_mov_b32_e32 v59, v0
	v_mov_b32_e32 v60, v0
	v_mov_b32_e32 v61, v0
	v_mov_b32_e32 v62, v0
	v_mov_b32_e32 v63, v0
	v_mov_b32_e32 v64, v0
	v_mov_b32_e32 v65, v0
	v_mov_b32_e32 v66, v0
	v_mov_b32_e32 v67, v0
	v_mov_b32_e32 v68, v0
	v_mov_b32_e32 v69, v0
	v_mov_b32_e32 v70, v0
	v_mov_b32_e32 v71, v0
	v_mov_b32_e32 v72, v0
	v_mov_b32_e32 v73, v0
	v_mov_b32_e32 v74, v0
	v_mov_b32_e32 v75, v0
	v_mov_b32_e32 v76, v0
	v_mov_b32_e32 v77, v0
	v_mov_b32_e32 v78, v0
	v_mov_b32_e32 v79, v0
	v_mov_b32_e32 v88, v0
	v_mov_b32_e32 v89, v0
	v_mov_b32_e32 v90, v0
	v_mov_b32_e32 v91, v0
	v_mov_b32_e32 v92, v0
	v_mov_b32_e32 v93, v0
	v_mov_b32_e32 v94, v0
	v_mov_b32_e32 v95, v0
	v_mov_b32_e32 v106, v0
	v_mov_b32_e32 v107, v0
	v_mov_b32_e32 v108, v0
	v_mov_b32_e32 v109, v0
	v_mov_b32_e32 v110, v0
	v_mov_b32_e32 v111, v0
	v_mov_b32_e32 v112, v0
	v_mov_b32_e32 v113, v0
	v_mov_b32_e32 v80, v0
	v_mov_b32_e32 v81, v0
	v_mov_b32_e32 v82, v0
	v_mov_b32_e32 v83, v0
	v_mov_b32_e32 v84, v0
	v_mov_b32_e32 v85, v0
	v_mov_b32_e32 v86, v0
	v_mov_b32_e32 v87, v0
	v_mov_b32_e32 v98, v0
	v_mov_b32_e32 v99, v0
	v_mov_b32_e32 v100, v0
	v_mov_b32_e32 v101, v0
	v_mov_b32_e32 v102, v0
	v_mov_b32_e32 v103, v0
	v_mov_b32_e32 v104, v0
	v_mov_b32_e32 v105, v0
	v_mov_b32_e32 v114, v0
	v_mov_b32_e32 v115, v0
	v_mov_b32_e32 v116, v0
	v_mov_b32_e32 v117, v0
	v_mov_b32_e32 v118, v0
	v_mov_b32_e32 v119, v0
	v_mov_b32_e32 v120, v0
	v_mov_b32_e32 v121, v0
	v_mov_b32_e32 v122, v0
	v_mov_b32_e32 v123, v0
	v_mov_b32_e32 v124, v0
	v_mov_b32_e32 v125, v0
	v_mov_b32_e32 v126, v0
	v_mov_b32_e32 v127, v0
	v_mov_b32_e32 v128, v0
	v_mov_b32_e32 v129, v0
	v_add_u32_e32 v155, 0x80, v96
	v_add_u32_e32 v157, 0x80, v130
	v_add_u32_e32 v199, 0x80, v134
	v_add_u32_e32 v203, 0x80, v132

.Lrx_ukv_1:
	s_waitcnt vmcnt(24)
	v_mov_b32_e32 v243, 0
	s_waitcnt lgkmcnt(0)
	s_setprio 1
	s_barrier
	v_mfma_f32_16x16x32_bf16 v[60:63], v[146:149], v[182:185], v[60:63]
	v_mfma_f32_16x16x32_bf16 v[56:59], v[158:161], v[182:185], v[56:59]
	v_mfma_f32_16x16x32_bf16 v[52:55], v[146:149], v[190:193], v[52:55]
	v_mfma_f32_16x16x32_bf16 v[48:51], v[158:161], v[190:193], v[48:51]
	v_mfma_f32_16x16x32_bf16 v[36:39], v[146:149], v[210:213], v[36:39]
	v_mfma_f32_16x16x32_bf16 v[32:35], v[158:161], v[210:213], v[32:35]
	v_mfma_f32_16x16x32_bf16 v[20:23], v[146:149], v[218:221], v[20:23]
	v_mfma_f32_16x16x32_bf16 v[16:19], v[158:161], v[218:221], v[16:19]
	v_mfma_f32_16x16x32_bf16 v[60:63], v[150:153], v[186:189], v[60:63]
	v_mfma_f32_16x16x32_bf16 v[56:59], v[162:165], v[186:189], v[56:59]
	v_mfma_f32_16x16x32_bf16 v[52:55], v[150:153], v[194:197], v[52:55]
	v_mfma_f32_16x16x32_bf16 v[48:51], v[162:165], v[194:197], v[48:51]
	v_mfma_f32_16x16x32_bf16 v[36:39], v[150:153], v[214:217], v[36:39]
	v_mfma_f32_16x16x32_bf16 v[32:35], v[162:165], v[214:217], v[32:35]
	v_mfma_f32_16x16x32_bf16 v[20:23], v[150:153], v[222:225], v[20:23]
	v_mfma_f32_16x16x32_bf16 v[16:19], v[162:165], v[222:225], v[16:19]
	v_mfma_f32_16x16x32_bf16 v[44:47], v[166:169], v[182:185], v[44:47]
	v_mfma_f32_16x16x32_bf16 v[40:43], v[174:177], v[182:185], v[40:43]
	v_mfma_f32_16x16x32_bf16 v[28:31], v[166:169], v[190:193], v[28:31]
	v_mfma_f32_16x16x32_bf16 v[24:27], v[174:177], v[190:193], v[24:27]
	v_mfma_f32_16x16x32_bf16 v[12:15], v[166:169], v[210:213], v[12:15]
	v_mfma_f32_16x16x32_bf16 v[8:11], v[174:177], v[210:213], v[8:11]
	v_mfma_f32_16x16x32_bf16 v[4:7], v[166:169], v[218:221], v[4:7]
	v_mfma_f32_16x16x32_bf16 v[0:3], v[174:177], v[218:221], v[0:3]
	v_mfma_f32_16x16x32_bf16 v[44:47], v[170:173], v[186:189], v[44:47]
	v_mfma_f32_16x16x32_bf16 v[40:43], v[178:181], v[186:189], v[40:43]
	v_mfma_f32_16x16x32_bf16 v[28:31], v[170:173], v[194:197], v[28:31]
	v_mfma_f32_16x16x32_bf16 v[24:27], v[178:181], v[194:197], v[24:27]
	v_mfma_f32_16x16x32_bf16 v[12:15], v[170:173], v[214:217], v[12:15]
	v_mfma_f32_16x16x32_bf16 v[8:11], v[178:181], v[214:217], v[8:11]
	v_mfma_f32_16x16x32_bf16 v[4:7], v[170:173], v[222:225], v[4:7]
	v_mfma_f32_16x16x32_bf16 v[0:3], v[178:181], v[222:225], v[0:3]
	s_barrier
	s_setprio 0
	s_add_i32 s61, 0, 0x18000
	v_add_u32_e32 v145, s61, v142
	s_add_i32 s62, 0, 0x1c000
	ds_read_b128 v[146:149], v145
	ds_read_b128 v[150:153], v145 offset:1024
	ds_read_b128 v[158:161], v145 offset:2048
	ds_read_b128 v[162:165], v145 offset:3072
	v_add_u32_e32 v145, s62, v142
	ds_read_b128 v[166:169], v145
	ds_read_b128 v[170:173], v145 offset:1024
	ds_read_b128 v[174:177], v145 offset:2048
	ds_read_b128 v[178:181], v145 offset:3072
	s_add_u32 s58, s84, 0x20000
	s_addc_u32 s59, s85, 0
	s_mov_b32 m0, s26
	ds_read_b128 v[182:185], v144 offset:32768
	ds_read_b128 v[186:189], v144 offset:33792
	ds_read_b128 v[190:193], v144 offset:34816
	ds_read_b128 v[194:197], v144 offset:35840
	ds_read_b128 v[210:213], v144 offset:36864
	ds_read_b128 v[214:217], v144 offset:37888
	ds_read_b128 v[218:221], v144 offset:38912
	ds_read_b128 v[222:225], v144 offset:39936
	global_load_lds_dwordx4 v134, s[58:59]
	s_mov_b32 m0, s27
	s_nop 0
	global_load_lds_dwordx4 v132, s[58:59]
	s_waitcnt vmcnt(8)
	s_waitcnt lgkmcnt(0)
	s_setprio 1
	s_barrier
	v_mfma_f32_16x16x32_bf16 v[126:129], v[146:149], v[182:185], v[126:129]
	v_mfma_f32_16x16x32_bf16 v[122:125], v[158:161], v[182:185], v[122:125]
	v_mfma_f32_16x16x32_bf16 v[118:121], v[146:149], v[190:193], v[118:121]
	v_mfma_f32_16x16x32_bf16 v[114:117], v[158:161], v[190:193], v[114:117]
	v_mfma_f32_16x16x32_bf16 v[102:105], v[146:149], v[210:213], v[102:105]
	v_mfma_f32_16x16x32_bf16 v[98:101], v[158:161], v[210:213], v[98:101]
	v_mfma_f32_16x16x32_bf16 v[84:87], v[146:149], v[218:221], v[84:87]
	v_mfma_f32_16x16x32_bf16 v[80:83], v[158:161], v[218:221], v[80:83]
	v_mfma_f32_16x16x32_bf16 v[126:129], v[150:153], v[186:189], v[126:129]
	v_mfma_f32_16x16x32_bf16 v[122:125], v[162:165], v[186:189], v[122:125]
	v_mfma_f32_16x16x32_bf16 v[118:121], v[150:153], v[194:197], v[118:121]
	v_mfma_f32_16x16x32_bf16 v[114:117], v[162:165], v[194:197], v[114:117]
	v_mfma_f32_16x16x32_bf16 v[102:105], v[150:153], v[214:217], v[102:105]
	v_mfma_f32_16x16x32_bf16 v[98:101], v[162:165], v[214:217], v[98:101]
	v_mfma_f32_16x16x32_bf16 v[84:87], v[150:153], v[222:225], v[84:87]
	v_mfma_f32_16x16x32_bf16 v[80:83], v[162:165], v[222:225], v[80:83]
	v_mfma_f32_16x16x32_bf16 v[110:113], v[166:169], v[182:185], v[110:113]
	v_mfma_f32_16x16x32_bf16 v[106:109], v[174:177], v[182:185], v[106:109]
	v_mfma_f32_16x16x32_bf16 v[92:95], v[166:169], v[190:193], v[92:95]
	v_mfma_f32_16x16x32_bf16 v[88:91], v[174:177], v[190:193], v[88:91]
	v_mfma_f32_16x16x32_bf16 v[76:79], v[166:169], v[210:213], v[76:79]
	v_mfma_f32_16x16x32_bf16 v[72:75], v[174:177], v[210:213], v[72:75]
	v_mfma_f32_16x16x32_bf16 v[68:71], v[166:169], v[218:221], v[68:71]
	v_mfma_f32_16x16x32_bf16 v[64:67], v[174:177], v[218:221], v[64:67]
	v_mfma_f32_16x16x32_bf16 v[110:113], v[170:173], v[186:189], v[110:113]
	v_mfma_f32_16x16x32_bf16 v[106:109], v[178:181], v[186:189], v[106:109]
	v_mfma_f32_16x16x32_bf16 v[92:95], v[170:173], v[194:197], v[92:95]
	v_mfma_f32_16x16x32_bf16 v[88:91], v[178:181], v[194:197], v[88:91]
	v_mfma_f32_16x16x32_bf16 v[76:79], v[170:173], v[214:217], v[76:79]
	v_mfma_f32_16x16x32_bf16 v[72:75], v[178:181], v[214:217], v[72:75]
	v_mfma_f32_16x16x32_bf16 v[68:71], v[170:173], v[222:225], v[68:71]
	v_mfma_f32_16x16x32_bf16 v[64:67], v[178:181], v[222:225], v[64:67]
	s_barrier
	s_setprio 0
	s_add_i32 s58, s61, s75
	s_mov_b32 m0, s58
	ds_read_b128 v[182:185], v144 offset:49152
	ds_read_b128 v[186:189], v144 offset:50176
	ds_read_b128 v[190:193], v144 offset:51200
	ds_read_b128 v[194:197], v144 offset:52224
	ds_read_b128 v[210:213], v144 offset:53248
	ds_read_b128 v[214:217], v144 offset:54272
	ds_read_b128 v[218:221], v144 offset:55296
	ds_read_b128 v[222:225], v144 offset:56320
	global_load_lds_dwordx4 v155, s[82:83]
	s_add_i32 m0, s58, 0x2000
	s_add_u32 s58, s82, 0x20080
	s_addc_u32 s59, s83, 0
	s_add_i32 s61, s62, s75
	global_load_lds_dwordx4 v157, s[82:83]
	s_mov_b32 m0, s61
	s_nop 0
	global_load_lds_dwordx4 v96, s[58:59]
	s_add_i32 m0, s61, 0x2000
	s_nop 0
	global_load_lds_dwordx4 v130, s[58:59]
	s_mov_b32 m0, s28
	s_nop 0
	global_load_lds_dwordx4 v199, s[84:85]
	s_mov_b32 m0, s33
	s_nop 0
	global_load_lds_dwordx4 v203, s[84:85]
	s_waitcnt vmcnt(8)
	s_waitcnt lgkmcnt(0)
	s_setprio 1
	s_barrier
	v_mfma_f32_16x16x32_bf16 v[60:63], v[146:149], v[182:185], v[60:63]
	v_mfma_f32_16x16x32_bf16 v[56:59], v[158:161], v[182:185], v[56:59]
	v_mfma_f32_16x16x32_bf16 v[52:55], v[146:149], v[190:193], v[52:55]
	v_mfma_f32_16x16x32_bf16 v[48:51], v[158:161], v[190:193], v[48:51]
	v_mfma_f32_16x16x32_bf16 v[36:39], v[146:149], v[210:213], v[36:39]
	v_mfma_f32_16x16x32_bf16 v[32:35], v[158:161], v[210:213], v[32:35]
	v_mfma_f32_16x16x32_bf16 v[20:23], v[146:149], v[218:221], v[20:23]
	v_mfma_f32_16x16x32_bf16 v[16:19], v[158:161], v[218:221], v[16:19]
	v_mfma_f32_16x16x32_bf16 v[60:63], v[150:153], v[186:189], v[60:63]
	v_mfma_f32_16x16x32_bf16 v[56:59], v[162:165], v[186:189], v[56:59]
	v_mfma_f32_16x16x32_bf16 v[52:55], v[150:153], v[194:197], v[52:55]
	v_mfma_f32_16x16x32_bf16 v[48:51], v[162:165], v[194:197], v[48:51]
	v_mfma_f32_16x16x32_bf16 v[36:39], v[150:153], v[214:217], v[36:39]
	v_mfma_f32_16x16x32_bf16 v[32:35], v[162:165], v[214:217], v[32:35]
	v_mfma_f32_16x16x32_bf16 v[20:23], v[150:153], v[222:225], v[20:23]
	v_mfma_f32_16x16x32_bf16 v[16:19], v[162:165], v[222:225], v[16:19]
	v_mfma_f32_16x16x32_bf16 v[44:47], v[166:169], v[182:185], v[44:47]
	v_mfma_f32_16x16x32_bf16 v[40:43], v[174:177], v[182:185], v[40:43]
	v_mfma_f32_16x16x32_bf16 v[28:31], v[166:169], v[190:193], v[28:31]
	v_mfma_f32_16x16x32_bf16 v[24:27], v[174:177], v[190:193], v[24:27]
	v_mfma_f32_16x16x32_bf16 v[12:15], v[166:169], v[210:213], v[12:15]
	v_mfma_f32_16x16x32_bf16 v[8:11], v[174:177], v[210:213], v[8:11]
	v_mfma_f32_16x16x32_bf16 v[4:7], v[166:169], v[218:221], v[4:7]
	v_mfma_f32_16x16x32_bf16 v[0:3], v[174:177], v[218:221], v[0:3]
	v_mfma_f32_16x16x32_bf16 v[44:47], v[170:173], v[186:189], v[44:47]
	v_mfma_f32_16x16x32_bf16 v[40:43], v[178:181], v[186:189], v[40:43]
	v_mfma_f32_16x16x32_bf16 v[28:31], v[170:173], v[194:197], v[28:31]
	v_mfma_f32_16x16x32_bf16 v[24:27], v[178:181], v[194:197], v[24:27]
	v_mfma_f32_16x16x32_bf16 v[12:15], v[170:173], v[214:217], v[12:15]
	v_mfma_f32_16x16x32_bf16 v[8:11], v[178:181], v[214:217], v[8:11]
	v_mfma_f32_16x16x32_bf16 v[4:7], v[170:173], v[222:225], v[4:7]
	v_mfma_f32_16x16x32_bf16 v[0:3], v[178:181], v[222:225], v[0:3]
	s_barrier
	s_setprio 0
	s_add_i32 s57, s57, 2
	s_add_u32 s68, s68, 0x100
	s_addc_u32 s69, s69, 0
	s_add_u32 s55, s55, 0x100
	s_addc_u32 s56, s56, 0
	s_cmp_gt_u32 s57, 5
	s_cbranch_scc0 .LBB0_656
	v_mov_b32_e32 v243, 1
	v_readlane_b32 s6, v251, 54
	v_readlane_b32 s7, v251, 55
	s_and_b64 vcc, exec, s[6:7]
	s_cbranch_vccz .LBB0_659
	s_barrier

.LBB0_1037:
	s_ashr_i32 s53, s52, 31
	s_lshl_b64 s[34:35], s[52:53], 20
	s_add_u32 s68, s50, s34
	s_addc_u32 s69, s51, s35
	s_and_b64 s[34:35], s[42:43], exec
	s_cselect_b32 s10, s69, s45
	s_cselect_b32 s12, s68, s44
	s_ashr_i32 s31, s30, 31
	s_lshl_b64 s[34:35], s[30:31], 20
	s_add_u32 s82, s46, s34
	s_addc_u32 s83, s47, s35
	s_and_b64 s[34:35], s[42:43], exec
	s_cselect_b32 s18, s83, s85
	s_cselect_b32 s20, s82, s84
	s_add_u32 s44, s44, 0x80080
	s_addc_u32 s45, s45, 0
	s_add_u32 s28, s84, 0x100
	v_mov_b32_e32 v0, 0
	s_addc_u32 s31, s85, 0
	s_mov_b32 s33, -2
	v_mov_b32_e32 v1, v0
	v_mov_b32_e32 v2, v0
	v_mov_b32_e32 v3, v0
	v_mov_b32_e32 v4, v0
	v_mov_b32_e32 v5, v0
	v_mov_b32_e32 v6, v0
	v_mov_b32_e32 v7, v0
	v_mov_b32_e32 v16, v0
	v_mov_b32_e32 v17, v0
	v_mov_b32_e32 v18, v0
	v_mov_b32_e32 v19, v0
	v_mov_b32_e32 v20, v0
	v_mov_b32_e32 v21, v0
	v_mov_b32_e32 v22, v0
	v_mov_b32_e32 v23, v0
	v_mov_b32_e32 v32, v0
	v_mov_b32_e32 v33, v0
	v_mov_b32_e32 v34, v0
	v_mov_b32_e32 v35, v0
	v_mov_b32_e32 v36, v0
	v_mov_b32_e32 v37, v0
	v_mov_b32_e32 v38, v0
	v_mov_b32_e32 v39, v0
	v_mov_b32_e32 v48, v0
	v_mov_b32_e32 v49, v0
	v_mov_b32_e32 v50, v0
	v_mov_b32_e32 v51, v0
	v_mov_b32_e32 v52, v0
	v_mov_b32_e32 v53, v0
	v_mov_b32_e32 v54, v0
	v_mov_b32_e32 v55, v0
	v_mov_b32_e32 v8, v0
	v_mov_b32_e32 v9, v0
	v_mov_b32_e32 v10, v0
	v_mov_b32_e32 v11, v0
	v_mov_b32_e32 v12, v0
	v_mov_b32_e32 v13, v0
	v_mov_b32_e32 v14, v0
	v_mov_b32_e32 v15, v0
	v_mov_b32_e32 v24, v0
	v_mov_b32_e32 v25, v0
	v_mov_b32_e32 v26, v0
	v_mov_b32_e32 v27, v0
	v_mov_b32_e32 v28, v0
	v_mov_b32_e32 v29, v0
	v_mov_b32_e32 v30, v0
	v_mov_b32_e32 v31, v0
	v_mov_b32_e32 v40, v0
	v_mov_b32_e32 v41, v0
	v_mov_b32_e32 v42, v0
	v_mov_b32_e32 v43, v0
	v_mov_b32_e32 v44, v0
	v_mov_b32_e32 v45, v0
	v_mov_b32_e32 v46, v0
	v_mov_b32_e32 v47, v0
	v_mov_b32_e32 v56, v0
	v_mov_b32_e32 v57, v0
	v_mov_b32_e32 v58, v0
	v_mov_b32_e32 v59, v0
	v_mov_b32_e32 v60, v0
	v_mov_b32_e32 v61, v0
	v_mov_b32_e32 v62, v0
	v_mov_b32_e32 v63, v0
	v_mov_b32_e32 v64, v0
	v_mov_b32_e32 v65, v0
	v_mov_b32_e32 v66, v0
	v_mov_b32_e32 v67, v0
	v_mov_b32_e32 v68, v0
	v_mov_b32_e32 v69, v0
	v_mov_b32_e32 v70, v0
	v_mov_b32_e32 v71, v0
	v_mov_b32_e32 v80, v0
	v_mov_b32_e32 v81, v0
	v_mov_b32_e32 v82, v0
	v_mov_b32_e32 v83, v0
	v_mov_b32_e32 v84, v0
	v_mov_b32_e32 v85, v0
	v_mov_b32_e32 v86, v0
	v_mov_b32_e32 v87, v0
	v_mov_b32_e32 v98, v0
	v_mov_b32_e32 v99, v0
	v_mov_b32_e32 v100, v0
	v_mov_b32_e32 v101, v0
	v_mov_b32_e32 v102, v0
	v_mov_b32_e32 v103, v0
	v_mov_b32_e32 v104, v0
	v_mov_b32_e32 v105, v0
	v_mov_b32_e32 v114, v0
	v_mov_b32_e32 v115, v0
	v_mov_b32_e32 v116, v0
	v_mov_b32_e32 v117, v0
	v_mov_b32_e32 v118, v0
	v_mov_b32_e32 v119, v0
	v_mov_b32_e32 v120, v0
	v_mov_b32_e32 v121, v0
	v_mov_b32_e32 v72, v0
	v_mov_b32_e32 v73, v0
	v_mov_b32_e32 v74, v0
	v_mov_b32_e32 v75, v0
	v_mov_b32_e32 v76, v0
	v_mov_b32_e32 v77, v0
	v_mov_b32_e32 v78, v0
	v_mov_b32_e32 v79, v0
	v_mov_b32_e32 v88, v0
	v_mov_b32_e32 v89, v0
	v_mov_b32_e32 v90, v0
	v_mov_b32_e32 v91, v0
	v_mov_b32_e32 v92, v0
	v_mov_b32_e32 v93, v0
	v_mov_b32_e32 v94, v0
	v_mov_b32_e32 v95, v0
	v_mov_b32_e32 v106, v0
	v_mov_b32_e32 v107, v0
	v_mov_b32_e32 v108, v0
	v_mov_b32_e32 v109, v0
	v_mov_b32_e32 v110, v0
	v_mov_b32_e32 v111, v0
	v_mov_b32_e32 v112, v0
	v_mov_b32_e32 v113, v0
	v_mov_b32_e32 v122, v0
	v_mov_b32_e32 v123, v0
	v_mov_b32_e32 v124, v0
	v_mov_b32_e32 v125, v0
	v_mov_b32_e32 v126, v0
	v_mov_b32_e32 v127, v0
	v_mov_b32_e32 v128, v0
	v_mov_b32_e32 v129, v0
	v_add_u32_e32 v165, 0x80, v96
	v_add_u32_e32 v223, 0x80, v142
	v_add_u32_e32 v225, 0x80, v146
	v_add_u32_e32 v227, 0x80, v144

.Lrx_G_OUT_1:
	s_waitcnt vmcnt(44)
	v_mov_b32_e32 v243, 0
	s_waitcnt lgkmcnt(0)
	s_setprio 1
	s_barrier
	v_mfma_f32_16x16x32_bf16 v[60:63], v[130:133], v[184:187], v[60:63]
	v_mfma_f32_16x16x32_bf16 v[56:59], v[152:155], v[184:187], v[56:59]
	v_mfma_f32_16x16x32_bf16 v[44:47], v[130:133], v[192:195], v[44:47]
	v_mfma_f32_16x16x32_bf16 v[40:43], v[152:155], v[192:195], v[40:43]
	v_mfma_f32_16x16x32_bf16 v[28:31], v[130:133], v[202:205], v[28:31]
	v_mfma_f32_16x16x32_bf16 v[24:27], v[152:155], v[202:205], v[24:27]
	v_mfma_f32_16x16x32_bf16 v[12:15], v[130:133], v[214:217], v[12:15]
	v_mfma_f32_16x16x32_bf16 v[8:11], v[152:155], v[214:217], v[8:11]
	v_mfma_f32_16x16x32_bf16 v[60:63], v[134:137], v[188:191], v[60:63]
	v_mfma_f32_16x16x32_bf16 v[56:59], v[156:159], v[188:191], v[56:59]
	v_mfma_f32_16x16x32_bf16 v[44:47], v[134:137], v[196:199], v[44:47]
	v_mfma_f32_16x16x32_bf16 v[40:43], v[156:159], v[196:199], v[40:43]
	v_mfma_f32_16x16x32_bf16 v[28:31], v[134:137], v[210:213], v[28:31]
	v_mfma_f32_16x16x32_bf16 v[24:27], v[156:159], v[210:213], v[24:27]
	v_mfma_f32_16x16x32_bf16 v[12:15], v[134:137], v[218:221], v[12:15]
	v_mfma_f32_16x16x32_bf16 v[8:11], v[156:159], v[218:221], v[8:11]
	v_mfma_f32_16x16x32_bf16 v[52:55], v[160:163], v[184:187], v[52:55]
	v_mfma_f32_16x16x32_bf16 v[48:51], v[176:179], v[184:187], v[48:51]
	v_mfma_f32_16x16x32_bf16 v[36:39], v[160:163], v[192:195], v[36:39]
	v_mfma_f32_16x16x32_bf16 v[32:35], v[176:179], v[192:195], v[32:35]
	v_mfma_f32_16x16x32_bf16 v[20:23], v[160:163], v[202:205], v[20:23]
	v_mfma_f32_16x16x32_bf16 v[16:19], v[176:179], v[202:205], v[16:19]
	v_mfma_f32_16x16x32_bf16 v[4:7], v[160:163], v[214:217], v[4:7]
	v_mfma_f32_16x16x32_bf16 v[0:3], v[176:179], v[214:217], v[0:3]
	v_mfma_f32_16x16x32_bf16 v[52:55], v[172:175], v[188:191], v[52:55]
	v_mfma_f32_16x16x32_bf16 v[48:51], v[180:183], v[188:191], v[48:51]
	v_mfma_f32_16x16x32_bf16 v[36:39], v[172:175], v[196:199], v[36:39]
	v_mfma_f32_16x16x32_bf16 v[32:35], v[180:183], v[196:199], v[32:35]
	v_mfma_f32_16x16x32_bf16 v[20:23], v[172:175], v[210:213], v[20:23]
	v_mfma_f32_16x16x32_bf16 v[16:19], v[180:183], v[210:213], v[16:19]
	v_mfma_f32_16x16x32_bf16 v[4:7], v[172:175], v[218:221], v[4:7]
	v_mfma_f32_16x16x32_bf16 v[0:3], v[180:183], v[218:221], v[0:3]
	s_barrier
	s_setprio 0
	s_add_i32 s38, 0, 0x18000
	s_add_i32 s39, 0, 0x1c000
	v_add_u32_e32 v156, s38, v169
	v_add_u32_e32 v180, s39, v169
	ds_read_b128 v[130:133], v156
	ds_read_b128 v[134:137], v156 offset:1024
	ds_read_b128 v[152:155], v156 offset:2048
	ds_read_b128 v[156:159], v156 offset:3072
	ds_read_b128 v[160:163], v180
	ds_read_b128 v[172:175], v180 offset:1024
	ds_read_b128 v[176:179], v180 offset:2048
	ds_read_b128 v[180:183], v180 offset:3072
	s_add_u32 s34, s86, 0x80000
	s_addc_u32 s35, s87, 0
	s_mov_b32 m0, s79
	ds_read_b128 v[184:187], v171 offset:32768
	ds_read_b128 v[188:191], v171 offset:33792
	ds_read_b128 v[192:195], v171 offset:34816
	ds_read_b128 v[196:199], v171 offset:35840
	ds_read_b128 v[202:205], v171 offset:36864
	ds_read_b128 v[210:213], v171 offset:37888
	ds_read_b128 v[214:217], v171 offset:38912
	ds_read_b128 v[218:221], v171 offset:39936
	global_load_lds_dwordx4 v146, s[34:35]
	s_mov_b32 m0, s90
	s_nop 0
	global_load_lds_dwordx4 v144, s[34:35]
	s_waitcnt vmcnt(8)
	s_waitcnt lgkmcnt(0)
	s_setprio 1
	s_barrier
	v_mfma_f32_16x16x32_bf16 v[126:129], v[130:133], v[184:187], v[126:129]
	v_mfma_f32_16x16x32_bf16 v[122:125], v[152:155], v[184:187], v[122:125]
	v_mfma_f32_16x16x32_bf16 v[110:113], v[130:133], v[192:195], v[110:113]
	v_mfma_f32_16x16x32_bf16 v[106:109], v[152:155], v[192:195], v[106:109]
	v_mfma_f32_16x16x32_bf16 v[92:95], v[130:133], v[202:205], v[92:95]
	v_mfma_f32_16x16x32_bf16 v[88:91], v[152:155], v[202:205], v[88:91]
	v_mfma_f32_16x16x32_bf16 v[76:79], v[130:133], v[214:217], v[76:79]
	v_mfma_f32_16x16x32_bf16 v[72:75], v[152:155], v[214:217], v[72:75]
	v_mfma_f32_16x16x32_bf16 v[126:129], v[134:137], v[188:191], v[126:129]
	v_mfma_f32_16x16x32_bf16 v[122:125], v[156:159], v[188:191], v[122:125]
	v_mfma_f32_16x16x32_bf16 v[110:113], v[134:137], v[196:199], v[110:113]
	v_mfma_f32_16x16x32_bf16 v[106:109], v[156:159], v[196:199], v[106:109]
	v_mfma_f32_16x16x32_bf16 v[92:95], v[134:137], v[210:213], v[92:95]
	v_mfma_f32_16x16x32_bf16 v[88:91], v[156:159], v[210:213], v[88:91]
	v_mfma_f32_16x16x32_bf16 v[76:79], v[134:137], v[218:221], v[76:79]
	v_mfma_f32_16x16x32_bf16 v[72:75], v[156:159], v[218:221], v[72:75]
	v_mfma_f32_16x16x32_bf16 v[118:121], v[160:163], v[184:187], v[118:121]
	v_mfma_f32_16x16x32_bf16 v[114:117], v[176:179], v[184:187], v[114:117]
	v_mfma_f32_16x16x32_bf16 v[102:105], v[160:163], v[192:195], v[102:105]
	v_mfma_f32_16x16x32_bf16 v[98:101], v[176:179], v[192:195], v[98:101]
	v_mfma_f32_16x16x32_bf16 v[84:87], v[160:163], v[202:205], v[84:87]
	v_mfma_f32_16x16x32_bf16 v[80:83], v[176:179], v[202:205], v[80:83]
	v_mfma_f32_16x16x32_bf16 v[68:71], v[160:163], v[214:217], v[68:71]
	v_mfma_f32_16x16x32_bf16 v[64:67], v[176:179], v[214:217], v[64:67]
	v_mfma_f32_16x16x32_bf16 v[118:121], v[172:175], v[188:191], v[118:121]
	v_mfma_f32_16x16x32_bf16 v[114:117], v[180:183], v[188:191], v[114:117]
	v_mfma_f32_16x16x32_bf16 v[102:105], v[172:175], v[196:199], v[102:105]
	v_mfma_f32_16x16x32_bf16 v[98:101], v[180:183], v[196:199], v[98:101]
	v_mfma_f32_16x16x32_bf16 v[84:87], v[172:175], v[210:213], v[84:87]
	v_mfma_f32_16x16x32_bf16 v[80:83], v[180:183], v[210:213], v[80:83]
	v_mfma_f32_16x16x32_bf16 v[68:71], v[172:175], v[218:221], v[68:71]
	v_mfma_f32_16x16x32_bf16 v[64:67], v[180:183], v[218:221], v[64:67]
	s_barrier
	s_setprio 0
	s_add_i32 s34, s38, s75
	s_mov_b32 m0, s34
	ds_read_b128 v[184:187], v171 offset:49152
	ds_read_b128 v[188:191], v171 offset:50176
	ds_read_b128 v[192:195], v171 offset:51200
	ds_read_b128 v[196:199], v171 offset:52224
	ds_read_b128 v[202:205], v171 offset:53248
	ds_read_b128 v[210:213], v171 offset:54272
	ds_read_b128 v[214:217], v171 offset:55296
	ds_read_b128 v[218:221], v171 offset:56320
	global_load_lds_dwordx4 v165, s[84:85]
	s_add_i32 m0, s34, 0x2000
	s_add_u32 s34, s84, 0x80080
	s_addc_u32 s35, s85, 0
	s_add_i32 s38, s39, s75
	global_load_lds_dwordx4 v223, s[84:85]
	s_mov_b32 m0, s38
	s_nop 0
	global_load_lds_dwordx4 v96, s[34:35]
	s_add_i32 m0, s38, 0x2000
	s_nop 0
	global_load_lds_dwordx4 v142, s[34:35]
	s_mov_b32 m0, s94
	s_nop 0
	global_load_lds_dwordx4 v225, s[86:87]
	s_mov_b32 m0, s95
	s_nop 0
	global_load_lds_dwordx4 v227, s[86:87]
	s_waitcnt vmcnt(8)
	s_waitcnt lgkmcnt(0)
	s_setprio 1
	s_barrier
	v_mfma_f32_16x16x32_bf16 v[60:63], v[130:133], v[184:187], v[60:63]
	v_mfma_f32_16x16x32_bf16 v[56:59], v[152:155], v[184:187], v[56:59]
	v_mfma_f32_16x16x32_bf16 v[44:47], v[130:133], v[192:195], v[44:47]
	v_mfma_f32_16x16x32_bf16 v[40:43], v[152:155], v[192:195], v[40:43]
	v_mfma_f32_16x16x32_bf16 v[28:31], v[130:133], v[202:205], v[28:31]
	v_mfma_f32_16x16x32_bf16 v[24:27], v[152:155], v[202:205], v[24:27]
	v_mfma_f32_16x16x32_bf16 v[12:15], v[130:133], v[214:217], v[12:15]
	v_mfma_f32_16x16x32_bf16 v[8:11], v[152:155], v[214:217], v[8:11]
	v_mfma_f32_16x16x32_bf16 v[60:63], v[134:137], v[188:191], v[60:63]
	v_mfma_f32_16x16x32_bf16 v[56:59], v[156:159], v[188:191], v[56:59]
	v_mfma_f32_16x16x32_bf16 v[44:47], v[134:137], v[196:199], v[44:47]
	v_mfma_f32_16x16x32_bf16 v[40:43], v[156:159], v[196:199], v[40:43]
	v_mfma_f32_16x16x32_bf16 v[28:31], v[134:137], v[210:213], v[28:31]
	v_mfma_f32_16x16x32_bf16 v[24:27], v[156:159], v[210:213], v[24:27]
	v_mfma_f32_16x16x32_bf16 v[12:15], v[134:137], v[218:221], v[12:15]
	v_mfma_f32_16x16x32_bf16 v[8:11], v[156:159], v[218:221], v[8:11]
	v_mfma_f32_16x16x32_bf16 v[52:55], v[160:163], v[184:187], v[52:55]
	v_mfma_f32_16x16x32_bf16 v[48:51], v[176:179], v[184:187], v[48:51]
	v_mfma_f32_16x16x32_bf16 v[36:39], v[160:163], v[192:195], v[36:39]
	v_mfma_f32_16x16x32_bf16 v[32:35], v[176:179], v[192:195], v[32:35]
	v_mfma_f32_16x16x32_bf16 v[20:23], v[160:163], v[202:205], v[20:23]
	v_mfma_f32_16x16x32_bf16 v[16:19], v[176:179], v[202:205], v[16:19]
	v_mfma_f32_16x16x32_bf16 v[4:7], v[160:163], v[214:217], v[4:7]
	v_mfma_f32_16x16x32_bf16 v[0:3], v[176:179], v[214:217], v[0:3]
	v_mfma_f32_16x16x32_bf16 v[52:55], v[172:175], v[188:191], v[52:55]
	v_mfma_f32_16x16x32_bf16 v[48:51], v[180:183], v[188:191], v[48:51]
	v_mfma_f32_16x16x32_bf16 v[36:39], v[172:175], v[196:199], v[36:39]
	v_mfma_f32_16x16x32_bf16 v[32:35], v[180:183], v[196:199], v[32:35]
	v_mfma_f32_16x16x32_bf16 v[20:23], v[172:175], v[210:213], v[20:23]
	v_mfma_f32_16x16x32_bf16 v[16:19], v[180:183], v[210:213], v[16:19]
	v_mfma_f32_16x16x32_bf16 v[4:7], v[172:175], v[218:221], v[4:7]
	v_mfma_f32_16x16x32_bf16 v[0:3], v[180:183], v[218:221], v[0:3]
	s_barrier
	s_setprio 0
	s_add_i32 s33, s33, 2
	s_add_u32 s44, s44, 0x100
	s_addc_u32 s45, s45, 0
	s_add_u32 s28, s28, 0x100
	s_addc_u32 s31, s31, 0
	s_cmp_gt_u32 s33, 29
	s_cbranch_scc0 .LBB0_1038
	v_mov_b32_e32 v243, 1
	v_readlane_b32 s0, v251, 54
	v_readlane_b32 s1, v251, 55
	s_and_b64 vcc, exec, s[0:1]
	s_cbranch_vccz .LBB0_1041
	s_barrier

.LBB0_1283:
	s_ashr_i32 s25, s24, 31
	s_lshl_b64 s[30:31], s[24:25], 20
	s_add_u32 s30, s10, s30
	s_addc_u32 s31, s27, s31
	s_and_b64 s[38:39], s[42:43], exec
	s_cselect_b32 s3, s31, s53
	s_cselect_b32 s12, s30, s52
	s_ashr_i32 s17, s16, 31
	s_lshl_b64 s[38:39], s[16:17], 20
	s_add_u32 s44, s14, s38
	s_addc_u32 s45, s26, s39
	s_and_b64 s[38:39], s[42:43], exec
	s_cselect_b32 s17, s45, s69
	s_cselect_b32 s18, s44, s68
	s_add_u32 s52, s52, 0x80080
	s_addc_u32 s53, s53, 0
	s_add_u32 s20, s68, 0x100
	v_mov_b32_e32 v0, 0
	s_addc_u32 s25, s69, 0
	s_mov_b32 s28, -2
	v_mov_b32_e32 v1, v0
	v_mov_b32_e32 v2, v0
	v_mov_b32_e32 v3, v0
	v_mov_b32_e32 v4, v0
	v_mov_b32_e32 v5, v0
	v_mov_b32_e32 v6, v0
	v_mov_b32_e32 v7, v0
	v_mov_b32_e32 v16, v0
	v_mov_b32_e32 v17, v0
	v_mov_b32_e32 v18, v0
	v_mov_b32_e32 v19, v0
	v_mov_b32_e32 v20, v0
	v_mov_b32_e32 v21, v0
	v_mov_b32_e32 v22, v0
	v_mov_b32_e32 v23, v0
	v_mov_b32_e32 v32, v0
	v_mov_b32_e32 v33, v0
	v_mov_b32_e32 v34, v0
	v_mov_b32_e32 v35, v0
	v_mov_b32_e32 v36, v0
	v_mov_b32_e32 v37, v0
	v_mov_b32_e32 v38, v0
	v_mov_b32_e32 v39, v0
	v_mov_b32_e32 v48, v0
	v_mov_b32_e32 v49, v0
	v_mov_b32_e32 v50, v0
	v_mov_b32_e32 v51, v0
	v_mov_b32_e32 v52, v0
	v_mov_b32_e32 v53, v0
	v_mov_b32_e32 v54, v0
	v_mov_b32_e32 v55, v0
	v_mov_b32_e32 v8, v0
	v_mov_b32_e32 v9, v0
	v_mov_b32_e32 v10, v0
	v_mov_b32_e32 v11, v0
	v_mov_b32_e32 v12, v0
	v_mov_b32_e32 v13, v0
	v_mov_b32_e32 v14, v0
	v_mov_b32_e32 v15, v0
	v_mov_b32_e32 v24, v0
	v_mov_b32_e32 v25, v0
	v_mov_b32_e32 v26, v0
	v_mov_b32_e32 v27, v0
	v_mov_b32_e32 v28, v0
	v_mov_b32_e32 v29, v0
	v_mov_b32_e32 v30, v0
	v_mov_b32_e32 v31, v0
	v_mov_b32_e32 v40, v0
	v_mov_b32_e32 v41, v0
	v_mov_b32_e32 v42, v0
	v_mov_b32_e32 v43, v0
	v_mov_b32_e32 v44, v0
	v_mov_b32_e32 v45, v0
	v_mov_b32_e32 v46, v0
	v_mov_b32_e32 v47, v0
	v_mov_b32_e32 v56, v0
	v_mov_b32_e32 v57, v0
	v_mov_b32_e32 v58, v0
	v_mov_b32_e32 v59, v0
	v_mov_b32_e32 v60, v0
	v_mov_b32_e32 v61, v0
	v_mov_b32_e32 v62, v0
	v_mov_b32_e32 v63, v0
	v_mov_b32_e32 v64, v0
	v_mov_b32_e32 v65, v0
	v_mov_b32_e32 v66, v0
	v_mov_b32_e32 v67, v0
	v_mov_b32_e32 v68, v0
	v_mov_b32_e32 v69, v0
	v_mov_b32_e32 v70, v0
	v_mov_b32_e32 v71, v0
	v_mov_b32_e32 v80, v0
	v_mov_b32_e32 v81, v0
	v_mov_b32_e32 v82, v0
	v_mov_b32_e32 v83, v0
	v_mov_b32_e32 v84, v0
	v_mov_b32_e32 v85, v0
	v_mov_b32_e32 v86, v0
	v_mov_b32_e32 v87, v0
	v_mov_b32_e32 v98, v0
	v_mov_b32_e32 v99, v0
	v_mov_b32_e32 v100, v0
	v_mov_b32_e32 v101, v0
	v_mov_b32_e32 v102, v0
	v_mov_b32_e32 v103, v0
	v_mov_b32_e32 v104, v0
	v_mov_b32_e32 v105, v0
	v_mov_b32_e32 v114, v0
	v_mov_b32_e32 v115, v0
	v_mov_b32_e32 v116, v0
	v_mov_b32_e32 v117, v0
	v_mov_b32_e32 v118, v0
	v_mov_b32_e32 v119, v0
	v_mov_b32_e32 v120, v0
	v_mov_b32_e32 v121, v0
	v_mov_b32_e32 v72, v0
	v_mov_b32_e32 v73, v0
	v_mov_b32_e32 v74, v0
	v_mov_b32_e32 v75, v0
	v_mov_b32_e32 v76, v0
	v_mov_b32_e32 v77, v0
	v_mov_b32_e32 v78, v0
	v_mov_b32_e32 v79, v0
	v_mov_b32_e32 v88, v0
	v_mov_b32_e32 v89, v0
	v_mov_b32_e32 v90, v0
	v_mov_b32_e32 v91, v0
	v_mov_b32_e32 v92, v0
	v_mov_b32_e32 v93, v0
	v_mov_b32_e32 v94, v0
	v_mov_b32_e32 v95, v0
	v_mov_b32_e32 v106, v0
	v_mov_b32_e32 v107, v0
	v_mov_b32_e32 v108, v0
	v_mov_b32_e32 v109, v0
	v_mov_b32_e32 v110, v0
	v_mov_b32_e32 v111, v0
	v_mov_b32_e32 v112, v0
	v_mov_b32_e32 v113, v0
	v_mov_b32_e32 v122, v0
	v_mov_b32_e32 v123, v0
	v_mov_b32_e32 v124, v0
	v_mov_b32_e32 v125, v0
	v_mov_b32_e32 v126, v0
	v_mov_b32_e32 v127, v0
	v_mov_b32_e32 v128, v0
	v_mov_b32_e32 v129, v0
	v_add_u32_e32 v145, 0x80, v96
	v_add_u32_e32 v199, 0x80, v134
	v_add_u32_e32 v227, 0x80, v138
	v_add_u32_e32 v229, 0x80, v136

.Lrx_G_UP_1:
	s_waitcnt vmcnt(24)
	v_mov_b32_e32 v243, 0
	s_waitcnt lgkmcnt(0)
	s_setprio 1
	s_barrier
	v_mfma_f32_16x16x32_bf16 v[60:63], v[154:157], v[186:189], v[60:63]
	v_mfma_f32_16x16x32_bf16 v[56:59], v[162:165], v[186:189], v[56:59]
	v_mfma_f32_16x16x32_bf16 v[44:47], v[154:157], v[194:197], v[44:47]
	v_mfma_f32_16x16x32_bf16 v[40:43], v[162:165], v[194:197], v[40:43]
	v_mfma_f32_16x16x32_bf16 v[28:31], v[154:157], v[210:213], v[28:31]
	v_mfma_f32_16x16x32_bf16 v[24:27], v[162:165], v[210:213], v[24:27]
	v_mfma_f32_16x16x32_bf16 v[12:15], v[154:157], v[218:221], v[12:15]
	v_mfma_f32_16x16x32_bf16 v[8:11], v[162:165], v[218:221], v[8:11]
	v_mfma_f32_16x16x32_bf16 v[60:63], v[158:161], v[190:193], v[60:63]
	v_mfma_f32_16x16x32_bf16 v[56:59], v[166:169], v[190:193], v[56:59]
	v_mfma_f32_16x16x32_bf16 v[44:47], v[158:161], v[202:205], v[44:47]
	v_mfma_f32_16x16x32_bf16 v[40:43], v[166:169], v[202:205], v[40:43]
	v_mfma_f32_16x16x32_bf16 v[28:31], v[158:161], v[214:217], v[28:31]
	v_mfma_f32_16x16x32_bf16 v[24:27], v[166:169], v[214:217], v[24:27]
	v_mfma_f32_16x16x32_bf16 v[12:15], v[158:161], v[222:225], v[12:15]
	v_mfma_f32_16x16x32_bf16 v[8:11], v[166:169], v[222:225], v[8:11]
	v_mfma_f32_16x16x32_bf16 v[52:55], v[170:173], v[186:189], v[52:55]
	v_mfma_f32_16x16x32_bf16 v[48:51], v[178:181], v[186:189], v[48:51]
	v_mfma_f32_16x16x32_bf16 v[36:39], v[170:173], v[194:197], v[36:39]
	v_mfma_f32_16x16x32_bf16 v[32:35], v[178:181], v[194:197], v[32:35]
	v_mfma_f32_16x16x32_bf16 v[20:23], v[170:173], v[210:213], v[20:23]
	v_mfma_f32_16x16x32_bf16 v[16:19], v[178:181], v[210:213], v[16:19]
	v_mfma_f32_16x16x32_bf16 v[4:7], v[170:173], v[218:221], v[4:7]
	v_mfma_f32_16x16x32_bf16 v[0:3], v[178:181], v[218:221], v[0:3]
	v_mfma_f32_16x16x32_bf16 v[52:55], v[174:177], v[190:193], v[52:55]
	v_mfma_f32_16x16x32_bf16 v[48:51], v[182:185], v[190:193], v[48:51]
	v_mfma_f32_16x16x32_bf16 v[36:39], v[174:177], v[202:205], v[36:39]
	v_mfma_f32_16x16x32_bf16 v[32:35], v[182:185], v[202:205], v[32:35]
	v_mfma_f32_16x16x32_bf16 v[20:23], v[174:177], v[214:217], v[20:23]
	v_mfma_f32_16x16x32_bf16 v[16:19], v[182:185], v[214:217], v[16:19]
	v_mfma_f32_16x16x32_bf16 v[4:7], v[174:177], v[222:225], v[4:7]
	v_mfma_f32_16x16x32_bf16 v[0:3], v[182:185], v[222:225], v[0:3]
	s_barrier
	s_setprio 0
	s_add_i32 s33, 0, 0x18000
	v_add_u32_e32 v153, s33, v150
	s_add_i32 s54, 0, 0x1c000
	ds_read_b128 v[154:157], v153
	ds_read_b128 v[158:161], v153 offset:1024
	ds_read_b128 v[162:165], v153 offset:2048
	ds_read_b128 v[166:169], v153 offset:3072
	v_add_u32_e32 v153, s54, v150
	ds_read_b128 v[170:173], v153
	ds_read_b128 v[174:177], v153 offset:1024
	ds_read_b128 v[178:181], v153 offset:2048
	ds_read_b128 v[182:185], v153 offset:3072
	s_add_u32 s38, s82, 0x80000
	s_addc_u32 s39, s83, 0
	s_mov_b32 m0, s50
	ds_read_b128 v[186:189], v152 offset:32768
	ds_read_b128 v[190:193], v152 offset:33792
	ds_read_b128 v[194:197], v152 offset:34816
	ds_read_b128 v[202:205], v152 offset:35840
	ds_read_b128 v[210:213], v152 offset:36864
	ds_read_b128 v[214:217], v152 offset:37888
	ds_read_b128 v[218:221], v152 offset:38912
	ds_read_b128 v[222:225], v152 offset:39936
	global_load_lds_dwordx4 v138, s[38:39]
	s_mov_b32 m0, s51
	s_nop 0
	global_load_lds_dwordx4 v136, s[38:39]
	s_waitcnt vmcnt(8)
	s_waitcnt lgkmcnt(0)
	s_setprio 1
	s_barrier
	v_mfma_f32_16x16x32_bf16 v[126:129], v[154:157], v[186:189], v[126:129]
	v_mfma_f32_16x16x32_bf16 v[122:125], v[162:165], v[186:189], v[122:125]
	v_mfma_f32_16x16x32_bf16 v[110:113], v[154:157], v[194:197], v[110:113]
	v_mfma_f32_16x16x32_bf16 v[106:109], v[162:165], v[194:197], v[106:109]
	v_mfma_f32_16x16x32_bf16 v[92:95], v[154:157], v[210:213], v[92:95]
	v_mfma_f32_16x16x32_bf16 v[88:91], v[162:165], v[210:213], v[88:91]
	v_mfma_f32_16x16x32_bf16 v[76:79], v[154:157], v[218:221], v[76:79]
	v_mfma_f32_16x16x32_bf16 v[72:75], v[162:165], v[218:221], v[72:75]
	v_mfma_f32_16x16x32_bf16 v[126:129], v[158:161], v[190:193], v[126:129]
	v_mfma_f32_16x16x32_bf16 v[122:125], v[166:169], v[190:193], v[122:125]
	v_mfma_f32_16x16x32_bf16 v[110:113], v[158:161], v[202:205], v[110:113]
	v_mfma_f32_16x16x32_bf16 v[106:109], v[166:169], v[202:205], v[106:109]
	v_mfma_f32_16x16x32_bf16 v[92:95], v[158:161], v[214:217], v[92:95]
	v_mfma_f32_16x16x32_bf16 v[88:91], v[166:169], v[214:217], v[88:91]
	v_mfma_f32_16x16x32_bf16 v[76:79], v[158:161], v[222:225], v[76:79]
	v_mfma_f32_16x16x32_bf16 v[72:75], v[166:169], v[222:225], v[72:75]
	v_mfma_f32_16x16x32_bf16 v[118:121], v[170:173], v[186:189], v[118:121]
	v_mfma_f32_16x16x32_bf16 v[114:117], v[178:181], v[186:189], v[114:117]
	v_mfma_f32_16x16x32_bf16 v[102:105], v[170:173], v[194:197], v[102:105]
	v_mfma_f32_16x16x32_bf16 v[98:101], v[178:181], v[194:197], v[98:101]
	v_mfma_f32_16x16x32_bf16 v[84:87], v[170:173], v[210:213], v[84:87]
	v_mfma_f32_16x16x32_bf16 v[80:83], v[178:181], v[210:213], v[80:83]
	v_mfma_f32_16x16x32_bf16 v[68:71], v[170:173], v[218:221], v[68:71]
	v_mfma_f32_16x16x32_bf16 v[64:67], v[178:181], v[218:221], v[64:67]
	v_mfma_f32_16x16x32_bf16 v[118:121], v[174:177], v[190:193], v[118:121]
	v_mfma_f32_16x16x32_bf16 v[114:117], v[182:185], v[190:193], v[114:117]
	v_mfma_f32_16x16x32_bf16 v[102:105], v[174:177], v[202:205], v[102:105]
	v_mfma_f32_16x16x32_bf16 v[98:101], v[182:185], v[202:205], v[98:101]
	v_mfma_f32_16x16x32_bf16 v[84:87], v[174:177], v[214:217], v[84:87]
	v_mfma_f32_16x16x32_bf16 v[80:83], v[182:185], v[214:217], v[80:83]
	v_mfma_f32_16x16x32_bf16 v[68:71], v[174:177], v[222:225], v[68:71]
	v_mfma_f32_16x16x32_bf16 v[64:67], v[182:185], v[222:225], v[64:67]
	s_barrier
	s_setprio 0
	s_add_i32 s33, s33, s75
	s_mov_b32 m0, s33
	ds_read_b128 v[186:189], v152 offset:49152
	ds_read_b128 v[190:193], v152 offset:50176
	ds_read_b128 v[194:197], v152 offset:51200
	ds_read_b128 v[202:205], v152 offset:52224
	ds_read_b128 v[210:213], v152 offset:53248
	ds_read_b128 v[214:217], v152 offset:54272
	ds_read_b128 v[218:221], v152 offset:55296
	ds_read_b128 v[222:225], v152 offset:56320
	global_load_lds_dwordx4 v145, s[68:69]
	s_add_i32 m0, s33, 0x2000
	s_add_u32 s38, s68, 0x80080
	s_addc_u32 s39, s69, 0
	s_add_i32 s33, s54, s75
	global_load_lds_dwordx4 v199, s[68:69]
	s_mov_b32 m0, s33
	s_nop 0
	global_load_lds_dwordx4 v96, s[38:39]
	s_add_i32 m0, s33, 0x2000
	s_nop 0
	global_load_lds_dwordx4 v134, s[38:39]
	s_mov_b32 m0, s58
	s_nop 0
	global_load_lds_dwordx4 v227, s[82:83]
	s_mov_b32 m0, s59
	s_nop 0
	global_load_lds_dwordx4 v229, s[82:83]
	s_waitcnt vmcnt(8)
	s_waitcnt lgkmcnt(0)
	s_setprio 1
	s_barrier
	v_mfma_f32_16x16x32_bf16 v[60:63], v[154:157], v[186:189], v[60:63]
	v_mfma_f32_16x16x32_bf16 v[56:59], v[162:165], v[186:189], v[56:59]
	v_mfma_f32_16x16x32_bf16 v[44:47], v[154:157], v[194:197], v[44:47]
	v_mfma_f32_16x16x32_bf16 v[40:43], v[162:165], v[194:197], v[40:43]
	v_mfma_f32_16x16x32_bf16 v[28:31], v[154:157], v[210:213], v[28:31]
	v_mfma_f32_16x16x32_bf16 v[24:27], v[162:165], v[210:213], v[24:27]
	v_mfma_f32_16x16x32_bf16 v[12:15], v[154:157], v[218:221], v[12:15]
	v_mfma_f32_16x16x32_bf16 v[8:11], v[162:165], v[218:221], v[8:11]
	v_mfma_f32_16x16x32_bf16 v[60:63], v[158:161], v[190:193], v[60:63]
	v_mfma_f32_16x16x32_bf16 v[56:59], v[166:169], v[190:193], v[56:59]
	v_mfma_f32_16x16x32_bf16 v[44:47], v[158:161], v[202:205], v[44:47]
	v_mfma_f32_16x16x32_bf16 v[40:43], v[166:169], v[202:205], v[40:43]
	v_mfma_f32_16x16x32_bf16 v[28:31], v[158:161], v[214:217], v[28:31]
	v_mfma_f32_16x16x32_bf16 v[24:27], v[166:169], v[214:217], v[24:27]
	v_mfma_f32_16x16x32_bf16 v[12:15], v[158:161], v[222:225], v[12:15]
	v_mfma_f32_16x16x32_bf16 v[8:11], v[166:169], v[222:225], v[8:11]
	v_mfma_f32_16x16x32_bf16 v[52:55], v[170:173], v[186:189], v[52:55]
	v_mfma_f32_16x16x32_bf16 v[48:51], v[178:181], v[186:189], v[48:51]
	v_mfma_f32_16x16x32_bf16 v[36:39], v[170:173], v[194:197], v[36:39]
	v_mfma_f32_16x16x32_bf16 v[32:35], v[178:181], v[194:197], v[32:35]
	v_mfma_f32_16x16x32_bf16 v[20:23], v[170:173], v[210:213], v[20:23]
	v_mfma_f32_16x16x32_bf16 v[16:19], v[178:181], v[210:213], v[16:19]
	v_mfma_f32_16x16x32_bf16 v[4:7], v[170:173], v[218:221], v[4:7]
	v_mfma_f32_16x16x32_bf16 v[0:3], v[178:181], v[218:221], v[0:3]
	v_mfma_f32_16x16x32_bf16 v[52:55], v[174:177], v[190:193], v[52:55]
	v_mfma_f32_16x16x32_bf16 v[48:51], v[182:185], v[190:193], v[48:51]
	v_mfma_f32_16x16x32_bf16 v[36:39], v[174:177], v[202:205], v[36:39]
	v_mfma_f32_16x16x32_bf16 v[32:35], v[182:185], v[202:205], v[32:35]
	v_mfma_f32_16x16x32_bf16 v[20:23], v[174:177], v[214:217], v[20:23]
	v_mfma_f32_16x16x32_bf16 v[16:19], v[182:185], v[214:217], v[16:19]
	v_mfma_f32_16x16x32_bf16 v[4:7], v[174:177], v[222:225], v[4:7]
	v_mfma_f32_16x16x32_bf16 v[0:3], v[182:185], v[222:225], v[0:3]
	s_barrier
	s_setprio 0
	s_add_i32 s28, s28, 2
	s_add_u32 s52, s52, 0x100
	s_addc_u32 s53, s53, 0
	s_add_u32 s20, s20, 0x100
	s_addc_u32 s25, s25, 0
	s_cmp_gt_u32 s28, 29
	s_cbranch_scc0 .LBB0_1284
	v_mov_b32_e32 v243, 1
	v_readlane_b32 s6, v251, 54
	v_readlane_b32 s7, v251, 55
	s_and_b64 vcc, exec, s[6:7]
	s_cbranch_vccz .LBB0_1287
	s_barrier
